# GU K-loop: first iteration peeled, first-touch MFMAs use C=0, no accumulator clear per tile
# speedup vs baseline: 1.0328x; 1.0065x over previous
; #define PG8_STAGE(bufoff, gbase, voff) do { _Pragma("unroll") for (int _i = 0; _i < 2; ++_i) \
;         __builtin_amdgcn_global_load_lds((const unsigned*)((const char*)(gbase) + (voff)[_i]), (LAS unsigned*)(lds + (bufoff) + ldsw + _i * 8192), 16, 0, 0); } while (0)
; #define PG8_LDA(dst, b, h) do { _Pragma("unroll") for (int m = 0; m < 4; ++m) _Pragma("unroll") for (int k = 0; k < 2; ++k) dst[m][k] = *(const LAS bf16x8*)(lds + PG8_SA(b, h) + aoff + m * 2048 + k * 1024); } while (0)
; #define PG8_LDB(dst, b, h) do { _Pragma("unroll") for (int n = 0; n < 2; ++n) _Pragma("unroll") for (int k = 0; k < 2; ++k) dst[n][k] = *(const LAS bf16x8*)(lds + PG8_SB(b, h) + boff + n * 2048 + k * 1024); } while (0)
; #define PG8_MMA(ai, bj, At, Bt) do { __builtin_amdgcn_s_setprio(1); _Pragma("unroll") for (int k = 0; k < 2; ++k) _Pragma("unroll") for (int m = 0; m < 4; ++m) _Pragma("unroll") for (int n = 0; n < 2; ++n) \
;         acc[ai][bj][m][n] = __builtin_amdgcn_mfma_f32_16x16x32_bf16(Bt[n][k], At[m][k], acc[ai][bj][m][n], 0, 0, 0); __builtin_amdgcn_s_setprio(0); } while (0)
; #define PG8_WAIT_V(n) asm volatile("s_waitcnt vmcnt(" #n ")" ::: "memory")
; #define PG8_WAIT_L(n) asm volatile("s_waitcnt lgkmcnt(" #n ")" ::: "memory")
; #define PG8_BAR __builtin_amdgcn_s_barrier()
; #define PG8_SCHED __builtin_amdgcn_sched_barrier(0)
; template <class Epi, bool ALIGN_EPI>
; __device__ __forceinline__ void gemm_phase(LAS unsigned char* lds, const Gemm g, const StaticOrder& S, const Epi& E, const int tid) {
;     ...
;         for (int t = 0; t < nt; t += 2) {
;             const bool last = (t == nt - 2);
;             const char* a1 = cA + (size_t)(t + 1) * kstep;
;             const char* a2 = last ? nA : cA + (size_t)(t + 2) * kstep; const char* b2 = last ? nB : cB + (size_t)(t + 2) * kstep;
;             const char* a3 = a2 + kstep; const char* b3 = b2 + kstep;
;             PG8_LDB(B0, 0, 0); PG8_LDB(B1, 0, 1); PG8_SCHED; PG8_LDA(At, 0, 0); PG8_STAGE(PG8_SA(1, 1), a1 + hA, voffA);
;             PG8_WAIT_V(8); PG8_WAIT_L(0); PG8_BAR; PG8_MMA(0, 0, At, B0); PG8_MMA(0, 1, At, B1); PG8_BAR; PG8_SCHED;
;             PG8_LDA(At, 0, 1); PG8_STAGE(PG8_SB(0, 0), b2, voffB); PG8_STAGE(PG8_SB(0, 1), b2 + hB, voffB); PG8_STAGE(PG8_SA(0, 0), a2, voffA);
;             PG8_WAIT_V(8); PG8_WAIT_L(0); PG8_BAR; PG8_MMA(1, 0, At, B0); PG8_MMA(1, 1, At, B1); PG8_BAR; PG8_SCHED;
.LBB0_306:
	s_andn2_b64 vcc, exec, s[36:37]
	s_cbranch_vccnz .LBB0_309
	v_lshl_add_u64 v[142:143], v[142:143], 0, s[92:93]
	v_lshl_add_u64 v[144:145], v[144:145], 0, s[80:81]
	s_mov_b32 s10, 0
.Lgu_first:
	s_add_i32 s11, s10, 2
	s_cmp_eq_u32 s58, s10
	v_lshl_add_u64 v[146:147], v[142:143], 0, s[92:93]
	s_cselect_b64 vcc, -1, 0
	v_add_u32_e32 v150, s33, v151
	s_add_i32 s10, 0, 0x14000
	v_cndmask_b32_e32 v167, v147, v139, vcc
	v_cndmask_b32_e32 v166, v146, v138, vcc
	ds_read_b128 v[146:149], v150
	ds_read_b128 v[154:157], v150 offset:1024
	ds_read_b128 v[158:161], v150 offset:2048
	ds_read_b128 v[162:165], v150 offset:3072
	v_add_u32_e32 v150, s10, v151
	ds_read_b128 v[176:179], v150
	ds_read_b128 v[180:183], v150 offset:1024
	ds_read_b128 v[184:187], v150 offset:2048
	ds_read_b128 v[188:191], v150 offset:3072
	v_cndmask_b32_e32 v221, v145, v141, vcc
	v_cndmask_b32_e32 v220, v144, v140, vcc
	v_lshl_add_u64 v[226:227], v[142:143], 0, v[134:135]
	s_add_i32 m0, s51, 0xc000
	ds_read_b128 v[192:195], v153
	ds_read_b128 v[196:199], v153 offset:1024
	ds_read_b128 v[200:203], v153 offset:2048
	ds_read_b128 v[204:207], v153 offset:3072
	ds_read_b128 v[208:211], v153 offset:4096
	ds_read_b128 v[212:215], v153 offset:5120
	ds_read_b128 v[216:219], v153 offset:6144
	ds_read_b128 v[240:243], v153 offset:7168
	global_load_lds_dwordx4 v[226:227], off
	v_lshl_add_u64 v[226:227], v[142:143], 0, v[136:137]
	s_add_i32 m0, s51, 0xe000
	s_nop 0
	global_load_lds_dwordx4 v[226:227], off
	s_waitcnt vmcnt(8)
	s_waitcnt lgkmcnt(0)
	s_barrier
	s_setprio 1
	s_waitcnt lgkmcnt(0)
	v_mfma_f32_16x16x32_bf16 v[120:123], v[146:149], v[192:195], 0
	v_mfma_f32_16x16x32_bf16 v[112:115], v[158:161], v[192:195], 0
	v_mfma_f32_16x16x32_bf16 v[104:107], v[146:149], v[200:203], 0
	v_mfma_f32_16x16x32_bf16 v[96:99], v[158:161], v[200:203], 0
	v_mfma_f32_16x16x32_bf16 v[88:91], v[146:149], v[208:211], 0
	v_mfma_f32_16x16x32_bf16 v[80:83], v[158:161], v[208:211], 0
	v_mfma_f32_16x16x32_bf16 v[72:75], v[146:149], v[216:219], 0
	v_mfma_f32_16x16x32_bf16 v[64:67], v[158:161], v[216:219], 0
	v_mfma_f32_16x16x32_bf16 v[120:123], v[154:157], v[196:199], v[120:123]
	v_mfma_f32_16x16x32_bf16 v[112:115], v[162:165], v[196:199], v[112:115]
	v_mfma_f32_16x16x32_bf16 v[104:107], v[154:157], v[204:207], v[104:107]
	v_mfma_f32_16x16x32_bf16 v[96:99], v[162:165], v[204:207], v[96:99]
	v_mfma_f32_16x16x32_bf16 v[88:91], v[154:157], v[212:215], v[88:91]
	v_mfma_f32_16x16x32_bf16 v[80:83], v[162:165], v[212:215], v[80:83]
	v_mfma_f32_16x16x32_bf16 v[72:75], v[154:157], v[240:243], v[72:75]
	v_mfma_f32_16x16x32_bf16 v[64:67], v[162:165], v[240:243], v[64:67]
	s_setprio 0
	s_setprio 1
	v_mfma_f32_16x16x32_bf16 v[124:127], v[176:179], v[192:195], 0
	v_mfma_f32_16x16x32_bf16 v[116:119], v[184:187], v[192:195], 0
	v_mfma_f32_16x16x32_bf16 v[108:111], v[176:179], v[200:203], 0
	v_mfma_f32_16x16x32_bf16 v[100:103], v[184:187], v[200:203], 0
	v_mfma_f32_16x16x32_bf16 v[92:95], v[176:179], v[208:211], 0
	v_mfma_f32_16x16x32_bf16 v[84:87], v[184:187], v[208:211], 0
	v_mfma_f32_16x16x32_bf16 v[76:79], v[176:179], v[216:219], 0
	v_mfma_f32_16x16x32_bf16 v[68:71], v[184:187], v[216:219], 0
	v_mfma_f32_16x16x32_bf16 v[124:127], v[180:183], v[196:199], v[124:127]
	v_mfma_f32_16x16x32_bf16 v[116:119], v[188:191], v[196:199], v[116:119]
	v_mfma_f32_16x16x32_bf16 v[108:111], v[180:183], v[204:207], v[108:111]
	v_mfma_f32_16x16x32_bf16 v[100:103], v[188:191], v[204:207], v[100:103]
	v_mfma_f32_16x16x32_bf16 v[92:95], v[180:183], v[212:215], v[92:95]
	v_mfma_f32_16x16x32_bf16 v[84:87], v[188:191], v[212:215], v[84:87]
	v_mfma_f32_16x16x32_bf16 v[76:79], v[180:183], v[240:243], v[76:79]
	v_mfma_f32_16x16x32_bf16 v[68:71], v[188:191], v[240:243], v[68:71]
	s_setprio 0
	s_barrier
	s_add_i32 s65, s33, s45
	v_lshl_add_u64 v[226:227], v[220:221], 0, v[168:169]
	s_mov_b32 m0, s65
	ds_read_b128 v[192:195], v153 offset:16384
	ds_read_b128 v[196:199], v153 offset:17408
	ds_read_b128 v[200:203], v153 offset:18432
	ds_read_b128 v[204:207], v153 offset:19456
	ds_read_b128 v[208:211], v153 offset:20480
	ds_read_b128 v[212:215], v153 offset:21504
	ds_read_b128 v[216:219], v153 offset:22528
	ds_read_b128 v[240:243], v153 offset:23552
	global_load_lds_dwordx4 v[226:227], off
	v_lshl_add_u64 v[244:245], v[220:221], 0, v[128:129]
	s_add_i32 m0, s65, 0x2000
	v_lshl_add_u64 v[220:221], v[220:221], 0, s[12:13]
	s_add_i32 s10, s10, s45
	global_load_lds_dwordx4 v[244:245], off
	v_lshl_add_u64 v[246:247], v[220:221], 0, v[168:169]
	s_mov_b32 m0, s10
	v_lshl_add_u64 v[220:221], v[220:221], 0, v[128:129]
	global_load_lds_dwordx4 v[246:247], off
	s_add_i32 m0, s10, 0x2000
	v_lshl_add_u64 v[248:249], v[166:167], 0, v[132:133]
	global_load_lds_dwordx4 v[220:221], off
	s_mov_b32 m0, s51
	v_lshl_add_u64 v[250:251], v[166:167], 0, v[130:131]
	global_load_lds_dwordx4 v[248:249], off
	s_mov_b32 m0, s52
	s_nop 0
	global_load_lds_dwordx4 v[250:251], off
	s_waitcnt vmcnt(8)
	s_waitcnt lgkmcnt(0)
	s_barrier
; #define PG8_STAGE(bufoff, gbase, voff) do { _Pragma("unroll") for (int _i = 0; _i < 2; ++_i) \
;         __builtin_amdgcn_global_load_lds((const unsigned*)((const char*)(gbase) + (voff)[_i]), (LAS unsigned*)(lds + (bufoff) + ldsw + _i * 8192), 16, 0, 0); } while (0)
; #define PG8_LDA(dst, b, h) do { _Pragma("unroll") for (int m = 0; m < 4; ++m) _Pragma("unroll") for (int k = 0; k < 2; ++k) dst[m][k] = *(const LAS bf16x8*)(lds + PG8_SA(b, h) + aoff + m * 2048 + k * 1024); } while (0)
; #define PG8_LDB(dst, b, h) do { _Pragma("unroll") for (int n = 0; n < 2; ++n) _Pragma("unroll") for (int k = 0; k < 2; ++k) dst[n][k] = *(const LAS bf16x8*)(lds + PG8_SB(b, h) + boff + n * 2048 + k * 1024); } while (0)
; #define PG8_MMA(ai, bj, At, Bt) do { __builtin_amdgcn_s_setprio(1); _Pragma("unroll") for (int k = 0; k < 2; ++k) _Pragma("unroll") for (int m = 0; m < 4; ++m) _Pragma("unroll") for (int n = 0; n < 2; ++n) \
;         acc[ai][bj][m][n] = __builtin_amdgcn_mfma_f32_16x16x32_bf16(Bt[n][k], At[m][k], acc[ai][bj][m][n], 0, 0, 0); __builtin_amdgcn_s_setprio(0); } while (0)
; #define PG8_WAIT_V(n) asm volatile("s_waitcnt vmcnt(" #n ")" ::: "memory")
; #define PG8_WAIT_L(n) asm volatile("s_waitcnt lgkmcnt(" #n ")" ::: "memory")
; #define PG8_BAR __builtin_amdgcn_s_barrier()
; #define PG8_SCHED __builtin_amdgcn_sched_barrier(0)
; template <class Epi, bool ALIGN_EPI>
; __device__ __forceinline__ void gemm_phase(LAS unsigned char* lds, const Gemm g, const StaticOrder& S, const Epi& E, const int tid) {
;     ...
;             PG8_LDA(At, 0, 1); PG8_STAGE(PG8_SB(0, 0), b2, voffB); PG8_STAGE(PG8_SB(0, 1), b2 + hB, voffB); PG8_STAGE(PG8_SA(0, 0), a2, voffA);
;             PG8_WAIT_V(8); PG8_WAIT_L(0); PG8_BAR; PG8_MMA(1, 0, At, B0); PG8_MMA(1, 1, At, B1); PG8_BAR; PG8_SCHED;
;             PG8_LDB(B0, 1, 0); PG8_LDB(B1, 1, 1); PG8_SCHED; PG8_LDA(At, 1, 0); PG8_STAGE(PG8_SA(0, 1), a2 + hA, voffA);
;             PG8_WAIT_V(8); PG8_WAIT_L(0); PG8_BAR; PG8_MMA(0, 0, At, B0); PG8_MMA(0, 1, At, B1); PG8_BAR; PG8_SCHED;
;             PG8_LDA(At, 1, 1); PG8_STAGE(PG8_SB(1, 0), b3, voffB); PG8_STAGE(PG8_SB(1, 1), b3 + hB, voffB); PG8_STAGE(PG8_SA(1, 0), a3, voffA);
	s_setprio 1
	s_waitcnt lgkmcnt(0)
	v_mfma_f32_16x16x32_bf16 v[56:59], v[146:149], v[192:195], 0
	v_mfma_f32_16x16x32_bf16 v[48:51], v[158:161], v[192:195], 0
	v_mfma_f32_16x16x32_bf16 v[40:43], v[146:149], v[200:203], 0
	v_mfma_f32_16x16x32_bf16 v[32:35], v[158:161], v[200:203], 0
	v_mfma_f32_16x16x32_bf16 v[24:27], v[146:149], v[208:211], 0
	v_mfma_f32_16x16x32_bf16 v[16:19], v[158:161], v[208:211], 0
	v_mfma_f32_16x16x32_bf16 v[8:11], v[146:149], v[216:219], 0
	v_mfma_f32_16x16x32_bf16 v[4:7], v[158:161], v[216:219], 0
	v_mfma_f32_16x16x32_bf16 v[56:59], v[154:157], v[196:199], v[56:59]
	v_mfma_f32_16x16x32_bf16 v[48:51], v[162:165], v[196:199], v[48:51]
	v_mfma_f32_16x16x32_bf16 v[40:43], v[154:157], v[204:207], v[40:43]
	v_mfma_f32_16x16x32_bf16 v[32:35], v[162:165], v[204:207], v[32:35]
	v_mfma_f32_16x16x32_bf16 v[24:27], v[154:157], v[212:215], v[24:27]
	v_mfma_f32_16x16x32_bf16 v[16:19], v[162:165], v[212:215], v[16:19]
	v_mfma_f32_16x16x32_bf16 v[8:11], v[154:157], v[240:243], v[8:11]
	v_mfma_f32_16x16x32_bf16 v[4:7], v[162:165], v[240:243], v[4:7]
	s_setprio 0
	s_setprio 1
	v_mfma_f32_16x16x32_bf16 v[60:63], v[176:179], v[192:195], 0
	v_mfma_f32_16x16x32_bf16 v[52:55], v[184:187], v[192:195], 0
	v_mfma_f32_16x16x32_bf16 v[44:47], v[176:179], v[200:203], 0
	v_mfma_f32_16x16x32_bf16 v[36:39], v[184:187], v[200:203], 0
	v_mfma_f32_16x16x32_bf16 v[28:31], v[176:179], v[208:211], 0
	v_mfma_f32_16x16x32_bf16 v[20:23], v[184:187], v[208:211], 0
	v_mfma_f32_16x16x32_bf16 v[12:15], v[176:179], v[216:219], 0
	v_mfma_f32_16x16x32_bf16 v[0:3], v[184:187], v[216:219], 0
	v_mfma_f32_16x16x32_bf16 v[60:63], v[180:183], v[196:199], v[60:63]
	v_mfma_f32_16x16x32_bf16 v[52:55], v[188:191], v[196:199], v[52:55]
	v_mfma_f32_16x16x32_bf16 v[44:47], v[180:183], v[204:207], v[44:47]
	v_mfma_f32_16x16x32_bf16 v[36:39], v[188:191], v[204:207], v[36:39]
	v_mfma_f32_16x16x32_bf16 v[28:31], v[180:183], v[212:215], v[28:31]
	v_mfma_f32_16x16x32_bf16 v[20:23], v[188:191], v[212:215], v[20:23]
	v_mfma_f32_16x16x32_bf16 v[12:15], v[180:183], v[240:243], v[12:15]
	v_mfma_f32_16x16x32_bf16 v[0:3], v[188:191], v[240:243], v[0:3]
	s_setprio 0
	s_barrier
	s_add_i32 s10, 0, 0x18000
	v_add_u32_e32 v150, s10, v151
	s_add_i32 s65, 0, 0x1c000
	ds_read_b128 v[146:149], v150
	ds_read_b128 v[154:157], v150 offset:1024
	ds_read_b128 v[158:161], v150 offset:2048
	ds_read_b128 v[162:165], v150 offset:3072
	v_add_u32_e32 v150, s65, v151
	ds_read_b128 v[176:179], v150
	ds_read_b128 v[180:183], v150 offset:1024
	ds_read_b128 v[184:187], v150 offset:2048
	ds_read_b128 v[188:191], v150 offset:3072
	v_lshl_add_u64 v[166:167], v[166:167], 0, s[94:95]
	s_mov_b32 m0, s53
	v_lshl_add_u64 v[252:253], v[166:167], 0, v[132:133]
	ds_read_b128 v[192:195], v153 offset:32768
	ds_read_b128 v[196:199], v153 offset:33792
	ds_read_b128 v[200:203], v153 offset:34816
	ds_read_b128 v[204:207], v153 offset:35840
	ds_read_b128 v[208:211], v153 offset:36864
	ds_read_b128 v[212:215], v153 offset:37888
	ds_read_b128 v[216:219], v153 offset:38912
	ds_read_b128 v[240:243], v153 offset:39936
	global_load_lds_dwordx4 v[252:253], off
	v_lshl_add_u64 v[166:167], v[166:167], 0, v[130:131]
	s_mov_b32 m0, s54
	s_nop 0
	global_load_lds_dwordx4 v[166:167], off
	s_waitcnt vmcnt(8)
	s_waitcnt lgkmcnt(0)
	s_barrier
	s_setprio 1
	s_waitcnt lgkmcnt(0)
	v_mfma_f32_16x16x32_bf16 v[120:123], v[146:149], v[192:195], v[120:123]
	v_mfma_f32_16x16x32_bf16 v[112:115], v[158:161], v[192:195], v[112:115]
	v_mfma_f32_16x16x32_bf16 v[104:107], v[146:149], v[200:203], v[104:107]
	v_mfma_f32_16x16x32_bf16 v[96:99], v[158:161], v[200:203], v[96:99]
	v_mfma_f32_16x16x32_bf16 v[88:91], v[146:149], v[208:211], v[88:91]
	v_mfma_f32_16x16x32_bf16 v[80:83], v[158:161], v[208:211], v[80:83]
	v_mfma_f32_16x16x32_bf16 v[72:75], v[146:149], v[216:219], v[72:75]
	v_mfma_f32_16x16x32_bf16 v[64:67], v[158:161], v[216:219], v[64:67]
	v_mfma_f32_16x16x32_bf16 v[120:123], v[154:157], v[196:199], v[120:123]
	v_mfma_f32_16x16x32_bf16 v[112:115], v[162:165], v[196:199], v[112:115]
	v_mfma_f32_16x16x32_bf16 v[104:107], v[154:157], v[204:207], v[104:107]
	v_mfma_f32_16x16x32_bf16 v[96:99], v[162:165], v[204:207], v[96:99]
	v_mfma_f32_16x16x32_bf16 v[88:91], v[154:157], v[212:215], v[88:91]
	v_mfma_f32_16x16x32_bf16 v[80:83], v[162:165], v[212:215], v[80:83]
	v_mfma_f32_16x16x32_bf16 v[72:75], v[154:157], v[240:243], v[72:75]
	v_mfma_f32_16x16x32_bf16 v[64:67], v[162:165], v[240:243], v[64:67]
	s_setprio 0
	s_setprio 1
	v_mfma_f32_16x16x32_bf16 v[124:127], v[176:179], v[192:195], v[124:127]
	v_mfma_f32_16x16x32_bf16 v[116:119], v[184:187], v[192:195], v[116:119]
	v_mfma_f32_16x16x32_bf16 v[108:111], v[176:179], v[200:203], v[108:111]
	v_mfma_f32_16x16x32_bf16 v[100:103], v[184:187], v[200:203], v[100:103]
	v_mfma_f32_16x16x32_bf16 v[92:95], v[176:179], v[208:211], v[92:95]
	v_mfma_f32_16x16x32_bf16 v[84:87], v[184:187], v[208:211], v[84:87]
	v_mfma_f32_16x16x32_bf16 v[76:79], v[176:179], v[216:219], v[76:79]
	v_mfma_f32_16x16x32_bf16 v[68:71], v[184:187], v[216:219], v[68:71]
	v_mfma_f32_16x16x32_bf16 v[124:127], v[180:183], v[196:199], v[124:127]
	v_mfma_f32_16x16x32_bf16 v[116:119], v[188:191], v[196:199], v[116:119]
	v_mfma_f32_16x16x32_bf16 v[108:111], v[180:183], v[204:207], v[108:111]
	v_mfma_f32_16x16x32_bf16 v[100:103], v[188:191], v[204:207], v[100:103]
	v_mfma_f32_16x16x32_bf16 v[92:95], v[180:183], v[212:215], v[92:95]
	v_mfma_f32_16x16x32_bf16 v[84:87], v[188:191], v[212:215], v[84:87]
	v_mfma_f32_16x16x32_bf16 v[76:79], v[180:183], v[240:243], v[76:79]
	v_mfma_f32_16x16x32_bf16 v[68:71], v[188:191], v[240:243], v[68:71]
	s_setprio 0
	s_barrier
; #define PG8_STAGE(bufoff, gbase, voff) do { _Pragma("unroll") for (int _i = 0; _i < 2; ++_i) \
;         __builtin_amdgcn_global_load_lds((const unsigned*)((const char*)(gbase) + (voff)[_i]), (LAS unsigned*)(lds + (bufoff) + ldsw + _i * 8192), 16, 0, 0); } while (0)
; #define PG8_LDA(dst, b, h) do { _Pragma("unroll") for (int m = 0; m < 4; ++m) _Pragma("unroll") for (int k = 0; k < 2; ++k) dst[m][k] = *(const LAS bf16x8*)(lds + PG8_SA(b, h) + aoff + m * 2048 + k * 1024); } while (0)
; #define PG8_MMA(ai, bj, At, Bt) do { __builtin_amdgcn_s_setprio(1); _Pragma("unroll") for (int k = 0; k < 2; ++k) _Pragma("unroll") for (int m = 0; m < 4; ++m) _Pragma("unroll") for (int n = 0; n < 2; ++n) \
;         acc[ai][bj][m][n] = __builtin_amdgcn_mfma_f32_16x16x32_bf16(Bt[n][k], At[m][k], acc[ai][bj][m][n], 0, 0, 0); __builtin_amdgcn_s_setprio(0); } while (0)
; #define PG8_WAIT_V(n) asm volatile("s_waitcnt vmcnt(" #n ")" ::: "memory")
; #define PG8_WAIT_L(n) asm volatile("s_waitcnt lgkmcnt(" #n ")" ::: "memory")
; #define PG8_BAR __builtin_amdgcn_s_barrier()
; #define PG8_SCHED __builtin_amdgcn_sched_barrier(0)
; template <class Epi, bool ALIGN_EPI>
; __device__ __forceinline__ void gemm_phase(LAS unsigned char* lds, const Gemm g, const StaticOrder& S, const Epi& E, const int tid) {
;     ...
;             PG8_LDA(At, 1, 1); PG8_STAGE(PG8_SB(1, 0), b3, voffB); PG8_STAGE(PG8_SB(1, 1), b3 + hB, voffB); PG8_STAGE(PG8_SA(1, 0), a3, voffA);
;             PG8_WAIT_V(8); PG8_WAIT_L(0); PG8_BAR; PG8_MMA(1, 0, At, B0); PG8_MMA(1, 1, At, B1); PG8_BAR; PG8_SCHED;
;         }
	s_add_i32 s10, s10, s45
	v_lshl_add_u64 v[166:167], v[226:227], 0, s[92:93]
	s_mov_b32 m0, s10
	ds_read_b128 v[192:195], v153 offset:49152
	ds_read_b128 v[196:199], v153 offset:50176
	ds_read_b128 v[200:203], v153 offset:51200
	ds_read_b128 v[204:207], v153 offset:52224
	ds_read_b128 v[208:211], v153 offset:53248
	ds_read_b128 v[212:215], v153 offset:54272
	ds_read_b128 v[216:219], v153 offset:55296
	ds_read_b128 v[240:243], v153 offset:56320
	global_load_lds_dwordx4 v[166:167], off
	v_lshl_add_u64 v[166:167], v[244:245], 0, s[92:93]
	s_add_i32 m0, s10, 0x2000
	s_add_i32 s10, s65, s45
	global_load_lds_dwordx4 v[166:167], off
	v_lshl_add_u64 v[166:167], v[246:247], 0, s[92:93]
	s_mov_b32 m0, s10
	s_nop 0
	global_load_lds_dwordx4 v[166:167], off
	v_lshl_add_u64 v[166:167], v[220:221], 0, s[92:93]
	s_add_i32 m0, s10, 0x2000
	s_nop 0
	global_load_lds_dwordx4 v[166:167], off
	v_lshl_add_u64 v[166:167], v[248:249], 0, s[92:93]
	s_mov_b32 m0, s56
	s_nop 0
	global_load_lds_dwordx4 v[166:167], off
	v_lshl_add_u64 v[166:167], v[250:251], 0, s[92:93]
	s_mov_b32 m0, s57
	s_nop 0
	global_load_lds_dwordx4 v[166:167], off
	s_waitcnt vmcnt(8)
	s_waitcnt lgkmcnt(0)
	s_barrier
	s_setprio 1
	s_waitcnt lgkmcnt(0)
	v_mfma_f32_16x16x32_bf16 v[56:59], v[146:149], v[192:195], v[56:59]
	v_mfma_f32_16x16x32_bf16 v[48:51], v[158:161], v[192:195], v[48:51]
	v_mfma_f32_16x16x32_bf16 v[40:43], v[146:149], v[200:203], v[40:43]
	v_mfma_f32_16x16x32_bf16 v[32:35], v[158:161], v[200:203], v[32:35]
	v_mfma_f32_16x16x32_bf16 v[24:27], v[146:149], v[208:211], v[24:27]
	v_mfma_f32_16x16x32_bf16 v[16:19], v[158:161], v[208:211], v[16:19]
	v_mfma_f32_16x16x32_bf16 v[8:11], v[146:149], v[216:219], v[8:11]
	v_mfma_f32_16x16x32_bf16 v[4:7], v[158:161], v[216:219], v[4:7]
	v_mfma_f32_16x16x32_bf16 v[56:59], v[154:157], v[196:199], v[56:59]
	v_mfma_f32_16x16x32_bf16 v[48:51], v[162:165], v[196:199], v[48:51]
	v_mfma_f32_16x16x32_bf16 v[40:43], v[154:157], v[204:207], v[40:43]
	v_mfma_f32_16x16x32_bf16 v[32:35], v[162:165], v[204:207], v[32:35]
	v_mfma_f32_16x16x32_bf16 v[24:27], v[154:157], v[212:215], v[24:27]
	v_mfma_f32_16x16x32_bf16 v[16:19], v[162:165], v[212:215], v[16:19]
	v_mfma_f32_16x16x32_bf16 v[8:11], v[154:157], v[240:243], v[8:11]
	v_mfma_f32_16x16x32_bf16 v[4:7], v[162:165], v[240:243], v[4:7]
	s_setprio 0
	s_setprio 1
	v_mfma_f32_16x16x32_bf16 v[60:63], v[176:179], v[192:195], v[60:63]
	v_mfma_f32_16x16x32_bf16 v[52:55], v[184:187], v[192:195], v[52:55]
	v_mfma_f32_16x16x32_bf16 v[44:47], v[176:179], v[200:203], v[44:47]
	v_mfma_f32_16x16x32_bf16 v[36:39], v[184:187], v[200:203], v[36:39]
	v_mfma_f32_16x16x32_bf16 v[28:31], v[176:179], v[208:211], v[28:31]
	v_mfma_f32_16x16x32_bf16 v[20:23], v[184:187], v[208:211], v[20:23]
	v_mfma_f32_16x16x32_bf16 v[12:15], v[176:179], v[216:219], v[12:15]
	v_mfma_f32_16x16x32_bf16 v[0:3], v[184:187], v[216:219], v[0:3]
	v_mfma_f32_16x16x32_bf16 v[60:63], v[180:183], v[196:199], v[60:63]
	v_mfma_f32_16x16x32_bf16 v[52:55], v[188:191], v[196:199], v[52:55]
	v_mfma_f32_16x16x32_bf16 v[44:47], v[180:183], v[204:207], v[44:47]
	v_mfma_f32_16x16x32_bf16 v[36:39], v[188:191], v[204:207], v[36:39]
	v_mfma_f32_16x16x32_bf16 v[28:31], v[180:183], v[212:215], v[28:31]
	v_mfma_f32_16x16x32_bf16 v[20:23], v[188:191], v[212:215], v[20:23]
	v_mfma_f32_16x16x32_bf16 v[12:15], v[180:183], v[240:243], v[12:15]
	v_mfma_f32_16x16x32_bf16 v[0:3], v[188:191], v[240:243], v[0:3]
	s_setprio 0
	s_barrier
	v_lshl_add_u64 v[142:143], v[142:143], 0, s[80:81]
	v_lshl_add_u64 v[144:145], v[144:145], 0, s[80:81]
	s_cmp_ge_u32 s11, s55
	s_mov_b32 s10, s11
	s_cbranch_scc1 .LBB0_309
